# grid barrier: skip the XCD L2 write-back after the residual-GEMM phases, whose stores are all write-through (sc1) or memory-side atomics
# speedup vs baseline: 1.0185x; 1.0001x over previous
; __device__ __forceinline__ unsigned xb_add(unsigned* p, unsigned v) { return __hip_atomic_fetch_add(p, v, __ATOMIC_RELAXED, __HIP_MEMORY_SCOPE_AGENT); }
; __device__ __forceinline__ void xcd_barrier(const XcdBarrier& b) {
;     ...
;         if (old + 1u == (gen + 1u) * nloc) {
;             __builtin_amdgcn_fence(__ATOMIC_RELEASE, "agent");
;             asm volatile("s_waitcnt vmcnt(0)" ::: "memory");
;             const unsigned og = xb_add(&bar[XB_TOP], 1u);
;             const unsigned tg = og / nx;
.LBB0_54:
	s_andn2_saveexec_b64 s[10:11], s[10:11]
	s_cbranch_execz .LBB0_74
	s_mov_b64 s[10:11], exec
	s_bitcmp1_b32 0x29548, s47
	s_cbranch_scc1 .Lxb_nowb
	buffer_wbl2 sc1
.Lxb_nowb:
	s_waitcnt lgkmcnt(0)
	s_waitcnt vmcnt(0)
	v_mbcnt_lo_u32_b32 v2, s10, 0
	v_mbcnt_hi_u32_b32 v2, s11, v2
	v_cmp_eq_u32_e32 vcc, 0, v2
	s_and_saveexec_b64 s[16:17], vcc
	s_cbranch_execz .LBB0_57
	s_bcnt1_i32_b64 s3, s[10:11]
	v_readlane_b32 s10, v252, 12
	v_mov_b32_e32 v3, s3
	v_readlane_b32 s11, v252, 13
	s_nop 4
	global_atomic_add v3, v1, v3, s[10:11] sc0
